# rglru depthwise conv re-mapped: thread = 4 channels x 4 tokens (3.6x less LDS read traffic), same FMA order
# speedup vs baseline: 1.0106x; 1.0106x over previous
.LBB0_1521:
	s_lshl_b32 s99, s6, 6
	s_add_i32 s11, s6, s73
	v_and_b32_e32 v98, 31, v154
	v_lshrrev_b32_e32 v99, 5, v154
	v_lshlrev_b32_e32 v136, 4, v98
	v_add_u32_e32 v136, 0xf0, v136
	v_lshlrev_b32_e32 v141, 3, v98
	v_add_u32_e32 v141, 0xf0, v141
	v_lshl_add_u32 v137, v99, 2, s99
	v_mov_b32_e32 v140, 0x110
	v_mad_u32_u24 v137, v137, v140, v141
	ds_read_b128 v[64:67], v136
	ds_read_b128 v[80:83], v136 offset:2048
	ds_read_b64 v[84:85], v137 offset:55296
	ds_read_b128 v[68:71], v136 offset:512
	ds_read_b64 v[86:87], v137 offset:55568
	ds_read_b128 v[72:75], v136 offset:1024
	ds_read_b64 v[88:89], v137 offset:55840
	ds_read_b128 v[76:79], v136 offset:1536
	ds_read_b64 v[90:91], v137 offset:56112
	ds_read_b64 v[92:93], v137 offset:56384
	ds_read_b64 v[94:95], v137 offset:56656
	ds_read_b64 v[96:97], v137 offset:56928
	v_and_b32_e32 v138, 3, v99
	v_lshlrev_b32_e32 v138, 4, v138
	v_lshrrev_b32_e32 v139, 2, v99
	v_lshl_add_u32 v98, v139, 2, v138
	v_mad_u32_u24 v139, v98, v140, v141
	v_mov_b32_e32 v140, 0x210
	v_mad_u32_u24 v138, v98, v140, v136
	s_waitcnt lgkmcnt(10)
	v_mov_b64_e32 v[100:101], v[80:81]
	v_mov_b64_e32 v[102:103], v[82:83]
	v_mov_b64_e32 v[104:105], v[80:81]
	v_mov_b64_e32 v[106:107], v[82:83]
	v_mov_b64_e32 v[108:109], v[80:81]
	v_mov_b64_e32 v[110:111], v[82:83]
	v_mov_b64_e32 v[112:113], v[80:81]
	v_mov_b64_e32 v[114:115], v[82:83]
	s_waitcnt lgkmcnt(9)
	v_lshlrev_b32_e32 v132, 16, v84
	v_and_b32_e32 v133, 0xffff0000, v84
	v_lshlrev_b32_e32 v134, 16, v85
	v_and_b32_e32 v135, 0xffff0000, v85
	v_fmac_f32_e32 v100, v132, v64
	v_fmac_f32_e32 v101, v133, v65
	v_fmac_f32_e32 v102, v134, v66
	v_fmac_f32_e32 v103, v135, v67
	s_waitcnt lgkmcnt(7)
	v_lshlrev_b32_e32 v132, 16, v86
	v_and_b32_e32 v133, 0xffff0000, v86
	v_lshlrev_b32_e32 v134, 16, v87
	v_and_b32_e32 v135, 0xffff0000, v87
	v_fmac_f32_e32 v104, v132, v64
	v_fmac_f32_e32 v105, v133, v65
	v_fmac_f32_e32 v106, v134, v66
	v_fmac_f32_e32 v107, v135, v67
	v_fmac_f32_e32 v100, v132, v68
	v_fmac_f32_e32 v101, v133, v69
	v_fmac_f32_e32 v102, v134, v70
	v_fmac_f32_e32 v103, v135, v71
	s_waitcnt lgkmcnt(5)
	v_lshlrev_b32_e32 v132, 16, v88
	v_and_b32_e32 v133, 0xffff0000, v88
	v_lshlrev_b32_e32 v134, 16, v89
	v_and_b32_e32 v135, 0xffff0000, v89
	v_fmac_f32_e32 v108, v132, v64
	v_fmac_f32_e32 v109, v133, v65
	v_fmac_f32_e32 v110, v134, v66
	v_fmac_f32_e32 v111, v135, v67
	v_fmac_f32_e32 v104, v132, v68
	v_fmac_f32_e32 v105, v133, v69
	v_fmac_f32_e32 v106, v134, v70
	v_fmac_f32_e32 v107, v135, v71
	v_fmac_f32_e32 v100, v132, v72
	v_fmac_f32_e32 v101, v133, v73
	v_fmac_f32_e32 v102, v134, v74
	v_fmac_f32_e32 v103, v135, v75
	s_waitcnt lgkmcnt(3)
	v_lshlrev_b32_e32 v132, 16, v90
	v_and_b32_e32 v133, 0xffff0000, v90
	v_lshlrev_b32_e32 v134, 16, v91
	v_and_b32_e32 v135, 0xffff0000, v91
	v_fmac_f32_e32 v112, v132, v64
	v_fmac_f32_e32 v113, v133, v65
	v_fmac_f32_e32 v114, v134, v66
	v_fmac_f32_e32 v115, v135, v67
	v_fmac_f32_e32 v108, v132, v68
	v_fmac_f32_e32 v109, v133, v69
	v_fmac_f32_e32 v110, v134, v70
	v_fmac_f32_e32 v111, v135, v71
	v_fmac_f32_e32 v104, v132, v72
	v_fmac_f32_e32 v105, v133, v73
	v_fmac_f32_e32 v106, v134, v74
	v_fmac_f32_e32 v107, v135, v75
	v_fmac_f32_e32 v100, v132, v76
	v_fmac_f32_e32 v101, v133, v77
	v_fmac_f32_e32 v102, v134, v78
	v_fmac_f32_e32 v103, v135, v79
	s_waitcnt lgkmcnt(2)
	v_lshlrev_b32_e32 v132, 16, v92
	v_and_b32_e32 v133, 0xffff0000, v92
	v_lshlrev_b32_e32 v134, 16, v93
	v_and_b32_e32 v135, 0xffff0000, v93
	v_fmac_f32_e32 v112, v132, v68
	v_fmac_f32_e32 v113, v133, v69
	v_fmac_f32_e32 v114, v134, v70
	v_fmac_f32_e32 v115, v135, v71
	v_fmac_f32_e32 v108, v132, v72
	v_fmac_f32_e32 v109, v133, v73
	v_fmac_f32_e32 v110, v134, v74
	v_fmac_f32_e32 v111, v135, v75
	v_fmac_f32_e32 v104, v132, v76
	v_fmac_f32_e32 v105, v133, v77
	v_fmac_f32_e32 v106, v134, v78
	v_fmac_f32_e32 v107, v135, v79
	s_waitcnt lgkmcnt(1)
	v_lshlrev_b32_e32 v132, 16, v94
	v_and_b32_e32 v133, 0xffff0000, v94
	v_lshlrev_b32_e32 v134, 16, v95
	v_and_b32_e32 v135, 0xffff0000, v95
	v_fmac_f32_e32 v112, v132, v72
	v_fmac_f32_e32 v113, v133, v73
	v_fmac_f32_e32 v114, v134, v74
	v_fmac_f32_e32 v115, v135, v75
	v_fmac_f32_e32 v108, v132, v76
	v_fmac_f32_e32 v109, v133, v77
	v_fmac_f32_e32 v110, v134, v78
	v_fmac_f32_e32 v111, v135, v79
	s_waitcnt lgkmcnt(0)
	v_lshlrev_b32_e32 v132, 16, v96
	v_and_b32_e32 v133, 0xffff0000, v96
	v_lshlrev_b32_e32 v134, 16, v97
	v_and_b32_e32 v135, 0xffff0000, v97
	v_fmac_f32_e32 v112, v132, v76
	v_fmac_f32_e32 v113, v133, v77
	v_fmac_f32_e32 v114, v134, v78
	v_fmac_f32_e32 v115, v135, v79
	ds_write_b128 v138, v[100:103] offset:4096
	ds_write_b128 v138, v[104:107] offset:4624
	ds_write_b128 v138, v[108:111] offset:5152
	ds_write_b128 v138, v[112:115] offset:5680
	v_cvt_pk_bf16_f32 v84, v100, v101
	v_cvt_pk_bf16_f32 v85, v102, v103
	v_cvt_pk_bf16_f32 v86, v104, v105
	v_cvt_pk_bf16_f32 v87, v106, v107
	v_cvt_pk_bf16_f32 v88, v108, v109
	v_cvt_pk_bf16_f32 v89, v110, v111
	v_cvt_pk_bf16_f32 v90, v112, v113
	v_cvt_pk_bf16_f32 v91, v114, v115
	ds_write_b64 v139, v[84:85] offset:37888
	ds_write_b64 v139, v[86:87] offset:38160
	ds_write_b64 v139, v[88:89] offset:38432
	ds_write_b64 v139, v[90:91] offset:38704
	s_waitcnt lgkmcnt(0)
	s_barrier
	ds_read_b128 v[64:67], v159 offset:37888
	ds_read_b128 v[68:71], v159 offset:37952
	ds_read_b128 v[84:87], v159 offset:42240
	ds_read_b128 v[88:91], v159 offset:42304
	ds_read_b128 v[104:107], v159 offset:46592
	ds_read_b128 v[108:111], v159 offset:46656
	ds_read_b128 v[140:143], v159 offset:50944
	ds_read_b128 v[144:147], v159 offset:51008
	s_waitcnt lgkmcnt(7)
	v_mfma_f32_16x16x32_bf16 v[72:75], v[64:67], v[0:3], 0
	v_mfma_f32_16x16x32_bf16 v[76:79], v[64:67], v[20:23], 0
	v_mfma_f32_16x16x32_bf16 v[80:83], v[64:67], v[36:39], 0
	v_mfma_f32_16x16x32_bf16 v[64:67], v[64:67], v[56:59], 0
	s_waitcnt lgkmcnt(5)
	v_mfma_f32_16x16x32_bf16 v[92:95], v[84:87], v[0:3], 0
	v_mfma_f32_16x16x32_bf16 v[96:99], v[84:87], v[20:23], 0
	v_mfma_f32_16x16x32_bf16 v[100:103], v[84:87], v[36:39], 0
	v_mfma_f32_16x16x32_bf16 v[84:87], v[84:87], v[56:59], 0
	s_waitcnt lgkmcnt(3)
	v_mfma_f32_16x16x32_bf16 v[112:115], v[104:107], v[0:3], 0
	v_mfma_f32_16x16x32_bf16 v[132:135], v[104:107], v[20:23], 0
	v_mfma_f32_16x16x32_bf16 v[136:139], v[104:107], v[36:39], 0
	v_mfma_f32_16x16x32_bf16 v[104:107], v[104:107], v[56:59], 0
	s_waitcnt lgkmcnt(1)
	v_mfma_f32_16x16x32_bf16 v[168:171], v[140:143], v[0:3], 0
	v_mfma_f32_16x16x32_bf16 v[172:175], v[140:143], v[20:23], 0
	v_mfma_f32_16x16x32_bf16 v[176:179], v[140:143], v[36:39], 0
	v_mfma_f32_16x16x32_bf16 v[140:143], v[140:143], v[56:59], 0
	v_mfma_f32_16x16x32_bf16 v[72:75], v[68:71], v[4:7], v[72:75]
	v_mfma_f32_16x16x32_bf16 v[76:79], v[68:71], v[16:19], v[76:79]
	v_mfma_f32_16x16x32_bf16 v[80:83], v[68:71], v[32:35], v[80:83]
	v_mfma_f32_16x16x32_bf16 v[64:67], v[68:71], v[48:51], v[64:67]
	v_mfma_f32_16x16x32_bf16 v[68:71], v[88:91], v[4:7], v[92:95]
	v_mfma_f32_16x16x32_bf16 v[92:95], v[88:91], v[16:19], v[96:99]
	v_mfma_f32_16x16x32_bf16 v[96:99], v[88:91], v[32:35], v[100:103]
	v_mfma_f32_16x16x32_bf16 v[84:87], v[88:91], v[48:51], v[84:87]
	v_mfma_f32_16x16x32_bf16 v[88:91], v[108:111], v[4:7], v[112:115]
	v_mfma_f32_16x16x32_bf16 v[100:103], v[108:111], v[16:19], v[132:135]
	v_mfma_f32_16x16x32_bf16 v[112:115], v[108:111], v[32:35], v[136:139]
	v_mfma_f32_16x16x32_bf16 v[104:107], v[108:111], v[48:51], v[104:107]
	s_waitcnt lgkmcnt(0)
	v_mfma_f32_16x16x32_bf16 v[108:111], v[144:147], v[4:7], v[168:171]
	v_mfma_f32_16x16x32_bf16 v[132:135], v[144:147], v[16:19], v[172:175]
	v_mfma_f32_16x16x32_bf16 v[136:139], v[144:147], v[32:35], v[176:179]
	v_mfma_f32_16x16x32_bf16 v[140:143], v[144:147], v[48:51], v[140:143]
	ds_read_b128 v[144:147], v159 offset:38016
	ds_read_b128 v[168:171], v159 offset:38080
	s_waitcnt lgkmcnt(1)
	v_mfma_f32_16x16x32_bf16 v[72:75], v[144:147], v[8:11], v[72:75]
	v_mfma_f32_16x16x32_bf16 v[76:79], v[144:147], v[24:27], v[76:79]
	v_mfma_f32_16x16x32_bf16 v[80:83], v[144:147], v[40:43], v[80:83]
	v_mfma_f32_16x16x32_bf16 v[64:67], v[144:147], v[52:55], v[64:67]
	ds_read_b128 v[144:147], v159 offset:42368
	ds_read_b128 v[172:175], v159 offset:42432
	s_waitcnt lgkmcnt(1)
	v_mfma_f32_16x16x32_bf16 v[176:179], v[144:147], v[8:11], v[68:71]
	s_nop 2
	ds_read_b128 v[68:71], v159 offset:46720
	ds_read_b128 v[188:191], v159 offset:46784
	v_mfma_f32_16x16x32_bf16 v[180:183], v[144:147], v[24:27], v[92:95]
	v_mfma_f32_16x16x32_bf16 v[184:187], v[144:147], v[40:43], v[96:99]
	v_mfma_f32_16x16x32_bf16 v[84:87], v[144:147], v[52:55], v[84:87]
	s_waitcnt lgkmcnt(1)
	v_mfma_f32_16x16x32_bf16 v[88:91], v[68:71], v[8:11], v[88:91]
	v_mfma_f32_16x16x32_bf16 v[144:147], v[68:71], v[24:27], v[100:103]
	v_mfma_f32_16x16x32_bf16 v[192:195], v[68:71], v[40:43], v[112:115]
	v_mfma_f32_16x16x32_bf16 v[196:199], v[68:71], v[52:55], v[104:107]
	ds_read_b128 v[68:71], v159 offset:51072
	ds_read_b128 v[92:95], v159 offset:51136
	s_waitcnt lgkmcnt(1)
	v_mfma_f32_16x16x32_bf16 v[200:203], v[68:71], v[8:11], v[108:111]
	v_mfma_f32_16x16x32_bf16 v[204:207], v[68:71], v[24:27], v[132:135]
	v_mfma_f32_16x16x32_bf16 v[208:211], v[68:71], v[40:43], v[136:139]
	v_mfma_f32_16x16x32_bf16 v[96:99], v[68:71], v[52:55], v[140:143]
	v_mfma_f32_16x16x32_bf16 v[68:71], v[168:171], v[44:47], v[80:83]
	s_nop 2
	v_add_u32_e32 v80, 0x3000, v160
	v_mfma_f32_16x16x32_bf16 v[112:115], v[172:175], v[12:15], v[176:179]
	ds_read2_b32 v[136:137], v80 offset0:64 offset1:196
	v_add_u32_e32 v80, 0x3400, v160
	ds_read2_b32 v[138:139], v80 offset0:72 offset1:204
	s_waitcnt lgkmcnt(2)
	v_mfma_f32_16x16x32_bf16 v[176:179], v[92:95], v[12:15], v[200:203]
	v_add_u32_e32 v80, 0x5200, v160
	ds_read2_b32 v[140:141], v80 offset1:132
	v_add_u32_e32 v80, 0x5600, v160
	v_mfma_f32_16x16x32_bf16 v[104:107], v[168:171], v[12:15], v[72:75]
	ds_read2_b32 v[142:143], v80 offset0:8 offset1:140
	v_add_u32_e32 v80, 0x7200, v160
	s_nop 1
	v_add_f32_e32 v176, v127, v176
	v_add_u32_e32 v72, 0x1000, v160
	ds_read2_b32 v[132:133], v72 offset1:132
	v_add_u32_e32 v72, 0x1400, v160
	v_mfma_f32_16x16x32_bf16 v[100:103], v[168:171], v[28:31], v[76:79]
	ds_read2_b32 v[134:135], v72 offset0:8 offset1:140
	v_exp_f32_e32 v176, v176
	v_add_f32_e32 v177, v127, v177
	v_mfma_f32_16x16x32_bf16 v[108:111], v[172:175], v[28:31], v[180:183]
	v_exp_f32_e32 v177, v177
	v_add_f32_e32 v176, 1.0, v176
	v_rcp_f32_e32 v176, v176
	v_mfma_f32_16x16x32_bf16 v[76:79], v[172:175], v[44:47], v[184:187]
	v_add_f32_e32 v177, 1.0, v177
	v_rcp_f32_e32 v177, v177
	v_mul_f32_e32 v176, v131, v176
	v_mfma_f32_16x16x32_bf16 v[72:75], v[172:175], v[60:63], v[84:87]
	v_exp_f32_e32 v176, v176
	v_mul_f32_e32 v177, v131, v177
	v_exp_f32_e32 v177, v177
	v_mfma_f32_16x16x32_bf16 v[172:175], v[188:191], v[28:31], v[144:147]
	v_add_u32_e32 v85, 0x7600, v160
	v_add_f32_e32 v114, v127, v114
	v_exp_f32_e32 v114, v114
	ds_read2_b32 v[144:145], v80 offset0:64 offset1:196
	v_add_f32_e32 v80, v127, v179
	v_exp_f32_e32 v84, v80
	v_mfma_f32_16x16x32_bf16 v[64:67], v[168:171], v[60:63], v[64:67]
	ds_read2_b32 v[146:147], v85 offset0:72 offset1:204
	v_add_f32_e32 v174, v129, v174
	v_add_f32_e32 v84, 1.0, v84
	v_rcp_f32_e32 v84, v84
	v_mfma_f32_16x16x32_bf16 v[168:171], v[188:191], v[12:15], v[88:91]
	v_exp_f32_e32 v174, v174
	v_add_f32_e32 v175, v129, v175
	v_exp_f32_e32 v175, v175
	v_mul_f32_e32 v88, v131, v84
	v_exp_f32_e32 v179, v88
	v_add_f32_e32 v88, v127, v178
	v_exp_f32_e32 v178, v88
	v_mfma_f32_16x16x32_bf16 v[180:183], v[92:95], v[28:31], v[204:207]
	v_add_f32_e32 v170, v127, v170
	v_exp_f32_e32 v170, v170
	v_add_f32_e32 v178, 1.0, v178
	v_rcp_f32_e32 v178, v178
	v_add_f32_e32 v171, v127, v171
	s_nop 2
	v_add_f32_e32 v182, v129, v182
	v_exp_f32_e32 v182, v182
	v_mul_f32_e32 v178, v131, v178
	v_exp_f32_e32 v178, v178
	v_add_f32_e32 v85, v129, v183
	v_exp_f32_e32 v167, v85
	v_exp_f32_e32 v171, v171
	v_fma_f32 v184, -v178, v178, 1.0
	v_add_f32_e32 v182, 1.0, v182
	v_max_f32_e32 v184, 0, v184
	v_fma_f32 v183, -v179, v179, 1.0
	v_rcp_f32_e32 v182, v182
	v_sqrt_f32_e32 v184, v184
	v_add_f32_e32 v180, v129, v180
	v_add_f32_e32 v170, 1.0, v170
	v_add_f32_e32 v167, 1.0, v167
	v_max_f32_e32 v183, 0, v183
	v_exp_f32_e32 v180, v180
	v_rcp_f32_e32 v170, v170
	v_add_f32_e32 v168, v127, v168
	v_rcp_f32_e32 v167, v167
	v_sqrt_f32_e32 v183, v183
	v_add_f32_e32 v181, v129, v181
	v_add_f32_e32 v171, 1.0, v171
	v_exp_f32_e32 v168, v168
	v_exp_f32_e32 v181, v181
	v_rcp_f32_e32 v171, v171
	v_add_f32_e32 v169, v127, v169
	v_mul_f32_e32 v182, v182, v184
	v_fma_f32 v184, -v176, v176, 1.0
	v_exp_f32_e32 v169, v169
	v_add_f32_e32 v180, 1.0, v180
	v_max_f32_e32 v184, 0, v184
	v_mul_f32_e32 v170, v131, v170
	v_mul_f32_e32 v167, v167, v183
	v_fma_f32 v183, -v177, v177, 1.0
	v_rcp_f32_e32 v180, v180
	v_sqrt_f32_e32 v184, v184
	v_exp_f32_e32 v170, v170
	v_add_f32_e32 v168, 1.0, v168
	v_add_f32_e32 v181, 1.0, v181
	v_max_f32_e32 v183, 0, v183
	v_mul_f32_e32 v171, v131, v171
	v_rcp_f32_e32 v168, v168
	v_rcp_f32_e32 v181, v181
	v_sqrt_f32_e32 v183, v183
	v_exp_f32_e32 v171, v171
	v_add_f32_e32 v169, 1.0, v169
	v_rcp_f32_e32 v169, v169
	v_add_f32_e32 v115, v127, v115
	v_mul_f32_e32 v180, v180, v184
	v_fma_f32 v184, -v170, v170, 1.0
	v_exp_f32_e32 v115, v115
	v_add_f32_e32 v174, 1.0, v174
	v_max_f32_e32 v184, 0, v184
	v_mul_f32_e32 v168, v131, v168
	v_mul_f32_e32 v181, v181, v183
	v_fma_f32 v183, -v171, v171, 1.0
	v_rcp_f32_e32 v174, v174
	v_sqrt_f32_e32 v184, v184
	v_add_f32_e32 v172, v129, v172
	v_exp_f32_e32 v168, v168
	v_add_f32_e32 v114, 1.0, v114
	v_add_f32_e32 v175, 1.0, v175
	v_max_f32_e32 v183, 0, v183
	v_mul_f32_e32 v169, v131, v169
	v_exp_f32_e32 v172, v172
	v_rcp_f32_e32 v114, v114
	v_add_f32_e32 v112, v127, v112
	v_rcp_f32_e32 v175, v175
	v_sqrt_f32_e32 v183, v183
	v_add_f32_e32 v173, v129, v173
	v_exp_f32_e32 v169, v169
	v_add_f32_e32 v115, 1.0, v115
	v_exp_f32_e32 v112, v112
	v_add_f32_e32 v104, v127, v104
	v_exp_f32_e32 v173, v173
	v_rcp_f32_e32 v115, v115
	v_add_f32_e32 v113, v127, v113
	v_exp_f32_e32 v104, v104
	v_mul_f32_e32 v174, v174, v184
	v_fma_f32 v184, -v168, v168, 1.0
	v_exp_f32_e32 v113, v113
	v_add_f32_e32 v172, 1.0, v172
	v_max_f32_e32 v184, 0, v184
	v_mul_f32_e32 v114, v131, v114
	v_add_f32_e32 v105, v127, v105
	v_mul_f32_e32 v175, v175, v183
	v_fma_f32 v183, -v169, v169, 1.0
	v_rcp_f32_e32 v172, v172
	v_sqrt_f32_e32 v184, v184
	v_add_f32_e32 v110, v129, v110
	v_exp_f32_e32 v114, v114
	v_add_f32_e32 v112, 1.0, v112
	v_exp_f32_e32 v105, v105
	v_add_f32_e32 v173, 1.0, v173
	v_max_f32_e32 v183, 0, v183
	v_mul_f32_e32 v115, v131, v115
	v_exp_f32_e32 v110, v110
	v_rcp_f32_e32 v112, v112
	v_add_f32_e32 v106, v127, v106
	v_add_f32_e32 v104, 1.0, v104
	v_rcp_f32_e32 v173, v173
	v_sqrt_f32_e32 v183, v183
	v_add_f32_e32 v111, v129, v111
	v_exp_f32_e32 v115, v115
	v_add_f32_e32 v113, 1.0, v113
	v_exp_f32_e32 v106, v106
	v_rcp_f32_e32 v104, v104
	v_exp_f32_e32 v111, v111
	v_rcp_f32_e32 v113, v113
	v_add_f32_e32 v107, v127, v107
	v_mul_f32_e32 v172, v172, v184
	v_fma_f32 v184, -v114, v114, 1.0
	v_exp_f32_e32 v107, v107
	v_add_f32_e32 v105, 1.0, v105
	v_add_f32_e32 v110, 1.0, v110
	v_max_f32_e32 v184, 0, v184
	v_mul_f32_e32 v112, v131, v112
	v_rcp_f32_e32 v105, v105
	v_mul_f32_e32 v173, v173, v183
	v_fma_f32 v183, -v115, v115, 1.0
	v_rcp_f32_e32 v110, v110
	v_sqrt_f32_e32 v184, v184
	v_add_f32_e32 v108, v129, v108
	v_exp_f32_e32 v112, v112
	v_add_f32_e32 v106, 1.0, v106
	v_mul_f32_e32 v104, v131, v104
	v_add_f32_e32 v111, 1.0, v111
	v_max_f32_e32 v183, 0, v183
	v_mul_f32_e32 v113, v131, v113
	v_exp_f32_e32 v108, v108
	v_rcp_f32_e32 v106, v106
	v_add_f32_e32 v100, v129, v100
	v_exp_f32_e32 v104, v104
	v_rcp_f32_e32 v111, v111
	v_sqrt_f32_e32 v183, v183
	v_add_f32_e32 v109, v129, v109
	v_exp_f32_e32 v113, v113
	v_add_f32_e32 v107, 1.0, v107
	v_exp_f32_e32 v100, v100
	v_exp_f32_e32 v109, v109
	v_rcp_f32_e32 v107, v107
	v_mul_f32_e32 v105, v131, v105
	v_mul_f32_e32 v110, v110, v184
	v_fma_f32 v184, -v112, v112, 1.0
	v_add_f32_e32 v101, v129, v101
	v_exp_f32_e32 v105, v105
	v_add_f32_e32 v108, 1.0, v108
	v_max_f32_e32 v184, 0, v184
	v_mul_f32_e32 v106, v131, v106
	v_exp_f32_e32 v101, v101
	v_fma_f32 v186, -v104, v104, 1.0
	v_mul_f32_e32 v111, v111, v183
	v_fma_f32 v183, -v113, v113, 1.0
	v_rcp_f32_e32 v108, v108
	v_sqrt_f32_e32 v184, v184
	v_add_f32_e32 v102, v129, v102
	v_exp_f32_e32 v106, v106
	v_add_f32_e32 v100, 1.0, v100
	v_max_f32_e32 v186, 0, v186
	v_add_f32_e32 v109, 1.0, v109
	v_max_f32_e32 v183, 0, v183
	v_mul_f32_e32 v107, v131, v107
	v_exp_f32_e32 v102, v102
	v_rcp_f32_e32 v100, v100
	v_sqrt_f32_e32 v186, v186
	v_rcp_f32_e32 v109, v109
	v_sqrt_f32_e32 v183, v183
	v_add_f32_e32 v103, v129, v103
	v_exp_f32_e32 v107, v107
	v_fma_f32 v185, -v105, v105, 1.0
	v_exp_f32_e32 v103, v103
	v_add_f32_e32 v101, 1.0, v101
	v_max_f32_e32 v185, 0, v185
	v_mul_f32_e32 v108, v108, v184
	v_fma_f32 v184, -v106, v106, 1.0
	v_rcp_f32_e32 v101, v101
	v_sqrt_f32_e32 v185, v185
	v_add_f32_e32 v102, 1.0, v102
	v_max_f32_e32 v184, 0, v184
	v_mul_f32_e32 v100, v100, v186
	v_mul_f32_e32 v109, v109, v183
	v_fma_f32 v183, -v107, v107, 1.0
	v_rcp_f32_e32 v102, v102
	v_sqrt_f32_e32 v184, v184
	s_waitcnt lgkmcnt(3)
	v_mul_f32_e32 v100, v100, v132
	v_add_f32_e32 v103, 1.0, v103
	v_max_f32_e32 v183, 0, v183
	v_fmac_f32_e32 v100, 0, v104
	v_rcp_f32_e32 v103, v103
	v_sqrt_f32_e32 v183, v183
	v_mul_f32_e32 v101, v101, v185
	v_mul_f32_e32 v100, v105, v100
	v_fmac_f32_e32 v100, v101, v133
	v_mul_f32_e32 v102, v102, v184
	v_mul_f32_e32 v100, v106, v100
	s_waitcnt lgkmcnt(2)
	v_fmac_f32_e32 v100, v102, v134
	v_mul_f32_e32 v103, v103, v183
	v_mul_f32_e32 v100, v107, v100
	v_fmac_f32_e32 v100, v103, v135
	v_mul_f32_e32 v100, v112, v100
	v_fmac_f32_e32 v100, v108, v136
	v_mul_f32_e32 v100, v113, v100
	v_fmac_f32_e32 v100, v109, v137
	v_mul_f32_e32 v100, v114, v100
	v_fmac_f32_e32 v100, v110, v138
	v_mul_f32_e32 v100, v115, v100
	v_fmac_f32_e32 v100, v111, v139
	v_mul_f32_e32 v100, v168, v100
	v_mul_f32_e32 v101, v104, v105
	v_fmac_f32_e32 v100, v172, v140
	v_mul_f32_e32 v101, v106, v101
	v_mul_f32_e32 v100, v169, v100
	v_mul_f32_e32 v101, v107, v101
	v_fmac_f32_e32 v100, v173, v141
	v_mul_f32_e32 v101, v101, v112
	v_mul_f32_e32 v100, v170, v100
	v_mul_f32_e32 v101, v113, v101
	v_fmac_f32_e32 v100, v174, v142
	v_mul_f32_e32 v101, v114, v101
	v_mul_f32_e32 v100, v171, v100
	v_mul_f32_e32 v101, v115, v101
	v_fmac_f32_e32 v100, v175, v143
	v_mul_f32_e32 v101, v101, v168
	v_mul_f32_e32 v100, v176, v100
	v_mul_f32_e32 v101, v169, v101
	s_waitcnt lgkmcnt(1)
	v_fmac_f32_e32 v100, v180, v144
	v_mul_f32_e32 v101, v170, v101
	v_mul_f32_e32 v100, v177, v100
	v_mul_f32_e32 v101, v171, v101
	v_fmac_f32_e32 v100, v181, v145
	v_mul_f32_e32 v101, v101, v176
	v_mul_f32_e32 v100, v178, v100
	v_mul_f32_e32 v101, v177, v101
	s_waitcnt lgkmcnt(0)
	v_fmac_f32_e32 v100, v182, v146
	v_mul_f32_e32 v101, v178, v101
	v_mul_f32_e32 v104, v179, v100
	v_fmac_f32_e32 v104, v167, v147
	v_mul_f32_e32 v103, v179, v101
	ds_bpermute_b32 v100, v162, v103
	ds_bpermute_b32 v102, v164, v103
	ds_bpermute_b32 v101, v165, v103
	ds_bpermute_b32 v103, v166, v103
	ds_bpermute_b32 v107, v162, v104
	ds_bpermute_b32 v106, v164, v104
	ds_bpermute_b32 v105, v165, v104
	ds_bpermute_b32 v104, v166, v104
	v_mfma_f32_16x16x32_bf16 v[80:83], v[188:191], v[44:47], v[192:195]
	v_mfma_f32_16x16x32_bf16 v[84:87], v[188:191], v[60:63], v[196:199]
	v_mfma_f32_16x16x32_bf16 v[88:91], v[92:95], v[44:47], v[208:211]
	v_mfma_f32_16x16x32_bf16 v[92:95], v[92:95], v[60:63], v[96:99]
	s_and_saveexec_b64 s[0:1], s[4:5]
	s_cbranch_execz .LBB0_1523
	s_waitcnt lgkmcnt(3)
	v_fmac_f32_e32 v107, 0, v100
	s_waitcnt lgkmcnt(2)
	v_fmac_f32_e32 v106, v107, v102
	s_waitcnt lgkmcnt(1)
	v_fmac_f32_e32 v105, v106, v101
	v_mul_f32_e64 v96, v100, v102
	v_mul_f32_e64 v97, v101, v103
	s_add_i32 s12, s11, s9
	s_waitcnt lgkmcnt(0)
	v_fmac_f32_e32 v104, v105, v103
	v_mad_i64_i32 v[98:99], s[12:13], s12, v163, v[124:125]
	v_pk_mul_f32 v[96:97], v[96:97], v[96:97] op_sel:[0,1] op_sel_hi:[1,0]
	v_lshl_add_u64 v[98:99], v[98:99], 3, s[36:37]
	v_mov_b32_e32 v97, v104
	global_store_dwordx2 v[98:99], v[96:97], off

.LBB0_1674:
	s_lshl_b32 s99, s0, 6
	s_add_i32 s15, s0, s12
	v_mad_i64_i32 v[64:65], s[16:17], s15, v197, v[178:179]
	s_addk_i32 s15, 0x210
	s_lshl_b32 s13, s0, 6
	global_load_dword v204, v[64:65], off
	v_mad_u64_u32 v[64:65], s[16:17], s15, v197, v[178:179]
	global_load_dword v203, v[64:65], off
	v_add_u32_e32 v202, s13, v198
	v_mov_b64_e32 v[64:65], s[36:37]
	v_mad_i64_i32 v[64:65], s[16:17], v202, s53, v[64:65]
	v_lshl_add_u64 v[64:65], s[76:77], 1, v[64:65]
	v_lshl_add_u64 v[64:65], v[64:65], 0, v[156:157]
	v_lshl_add_u64 v[66:67], v[64:65], 0, s[74:75]
	v_add_co_u32_e32 v64, vcc, s88, v64
	v_addc_co_u32_e32 v65, vcc, 0, v65, vcc
	global_load_dwordx4 v[68:71], v[64:65], off offset:2560
	s_nop 0
	global_load_dwordx4 v[64:67], v[66:67], off offset:16
	s_add_i32 s0, s0, 1
	v_and_b32_e32 v106, 31, v154
	v_lshrrev_b32_e32 v107, 5, v154
	v_lshlrev_b32_e32 v128, 4, v106
	v_add_u32_e32 v128, 0xf0, v128
	v_lshlrev_b32_e32 v133, 3, v106
	v_add_u32_e32 v133, 0xf0, v133
	v_lshl_add_u32 v129, v107, 2, s99
	v_mov_b32_e32 v132, 0x110
	v_mad_u32_u24 v129, v129, v132, v133
	ds_read_b128 v[72:75], v128
	ds_read_b128 v[88:91], v128 offset:2048
	ds_read_b64 v[92:93], v129 offset:55296
	ds_read_b128 v[76:79], v128 offset:512
	ds_read_b64 v[94:95], v129 offset:55568
	ds_read_b128 v[80:83], v128 offset:1024
	ds_read_b64 v[96:97], v129 offset:55840
	ds_read_b128 v[84:87], v128 offset:1536
	ds_read_b64 v[98:99], v129 offset:56112
	ds_read_b64 v[100:101], v129 offset:56384
	ds_read_b64 v[102:103], v129 offset:56656
	ds_read_b64 v[104:105], v129 offset:56928
	v_and_b32_e32 v130, 3, v107
	v_lshlrev_b32_e32 v130, 4, v130
	v_lshrrev_b32_e32 v131, 2, v107
	v_lshl_add_u32 v106, v131, 2, v130
	v_mad_u32_u24 v131, v106, v132, v133
	v_mov_b32_e32 v132, 0x210
	v_mad_u32_u24 v130, v106, v132, v128
	s_waitcnt lgkmcnt(10)
	v_mov_b64_e32 v[108:109], v[88:89]
	v_mov_b64_e32 v[110:111], v[90:91]
	v_mov_b64_e32 v[112:113], v[88:89]
	v_mov_b64_e32 v[114:115], v[90:91]
	v_mov_b64_e32 v[116:117], v[88:89]
	v_mov_b64_e32 v[118:119], v[90:91]
	v_mov_b64_e32 v[120:121], v[88:89]
	v_mov_b64_e32 v[122:123], v[90:91]
	s_waitcnt lgkmcnt(9)
	v_lshlrev_b32_e32 v124, 16, v92
	v_and_b32_e32 v125, 0xffff0000, v92
	v_lshlrev_b32_e32 v126, 16, v93
	v_and_b32_e32 v127, 0xffff0000, v93
	v_fmac_f32_e32 v108, v124, v72
	v_fmac_f32_e32 v109, v125, v73
	v_fmac_f32_e32 v110, v126, v74
	v_fmac_f32_e32 v111, v127, v75
	s_waitcnt lgkmcnt(7)
	v_lshlrev_b32_e32 v124, 16, v94
	v_and_b32_e32 v125, 0xffff0000, v94
	v_lshlrev_b32_e32 v126, 16, v95
	v_and_b32_e32 v127, 0xffff0000, v95
	v_fmac_f32_e32 v112, v124, v72
	v_fmac_f32_e32 v113, v125, v73
	v_fmac_f32_e32 v114, v126, v74
	v_fmac_f32_e32 v115, v127, v75
	v_fmac_f32_e32 v108, v124, v76
	v_fmac_f32_e32 v109, v125, v77
	v_fmac_f32_e32 v110, v126, v78
	v_fmac_f32_e32 v111, v127, v79
	s_waitcnt lgkmcnt(5)
	v_lshlrev_b32_e32 v124, 16, v96
	v_and_b32_e32 v125, 0xffff0000, v96
	v_lshlrev_b32_e32 v126, 16, v97
	v_and_b32_e32 v127, 0xffff0000, v97
	v_fmac_f32_e32 v116, v124, v72
	v_fmac_f32_e32 v117, v125, v73
	v_fmac_f32_e32 v118, v126, v74
	v_fmac_f32_e32 v119, v127, v75
	v_fmac_f32_e32 v112, v124, v76
	v_fmac_f32_e32 v113, v125, v77
	v_fmac_f32_e32 v114, v126, v78
	v_fmac_f32_e32 v115, v127, v79
	v_fmac_f32_e32 v108, v124, v80
	v_fmac_f32_e32 v109, v125, v81
	v_fmac_f32_e32 v110, v126, v82
	v_fmac_f32_e32 v111, v127, v83
	s_waitcnt lgkmcnt(3)
	v_lshlrev_b32_e32 v124, 16, v98
	v_and_b32_e32 v125, 0xffff0000, v98
	v_lshlrev_b32_e32 v126, 16, v99
	v_and_b32_e32 v127, 0xffff0000, v99
	v_fmac_f32_e32 v120, v124, v72
	v_fmac_f32_e32 v121, v125, v73
	v_fmac_f32_e32 v122, v126, v74
	v_fmac_f32_e32 v123, v127, v75
	v_fmac_f32_e32 v116, v124, v76
	v_fmac_f32_e32 v117, v125, v77
	v_fmac_f32_e32 v118, v126, v78
	v_fmac_f32_e32 v119, v127, v79
	v_fmac_f32_e32 v112, v124, v80
	v_fmac_f32_e32 v113, v125, v81
	v_fmac_f32_e32 v114, v126, v82
	v_fmac_f32_e32 v115, v127, v83
	v_fmac_f32_e32 v108, v124, v84
	v_fmac_f32_e32 v109, v125, v85
	v_fmac_f32_e32 v110, v126, v86
	v_fmac_f32_e32 v111, v127, v87
	s_waitcnt lgkmcnt(2)
	v_lshlrev_b32_e32 v124, 16, v100
	v_and_b32_e32 v125, 0xffff0000, v100
	v_lshlrev_b32_e32 v126, 16, v101
	v_and_b32_e32 v127, 0xffff0000, v101
	v_fmac_f32_e32 v120, v124, v76
	v_fmac_f32_e32 v121, v125, v77
	v_fmac_f32_e32 v122, v126, v78
	v_fmac_f32_e32 v123, v127, v79
	v_fmac_f32_e32 v116, v124, v80
	v_fmac_f32_e32 v117, v125, v81
	v_fmac_f32_e32 v118, v126, v82
	v_fmac_f32_e32 v119, v127, v83
	v_fmac_f32_e32 v112, v124, v84
	v_fmac_f32_e32 v113, v125, v85
	v_fmac_f32_e32 v114, v126, v86
	v_fmac_f32_e32 v115, v127, v87
	s_waitcnt lgkmcnt(1)
	v_lshlrev_b32_e32 v124, 16, v102
	v_and_b32_e32 v125, 0xffff0000, v102
	v_lshlrev_b32_e32 v126, 16, v103
	v_and_b32_e32 v127, 0xffff0000, v103
	v_fmac_f32_e32 v120, v124, v80
	v_fmac_f32_e32 v121, v125, v81
	v_fmac_f32_e32 v122, v126, v82
	v_fmac_f32_e32 v123, v127, v83
	v_fmac_f32_e32 v116, v124, v84
	v_fmac_f32_e32 v117, v125, v85
	v_fmac_f32_e32 v118, v126, v86
	v_fmac_f32_e32 v119, v127, v87
	s_waitcnt lgkmcnt(0)
	v_lshlrev_b32_e32 v124, 16, v104
	v_and_b32_e32 v125, 0xffff0000, v104
	v_lshlrev_b32_e32 v126, 16, v105
	v_and_b32_e32 v127, 0xffff0000, v105
	v_fmac_f32_e32 v120, v124, v84
	v_fmac_f32_e32 v121, v125, v85
	v_fmac_f32_e32 v122, v126, v86
	v_fmac_f32_e32 v123, v127, v87
	ds_write_b128 v130, v[108:111] offset:4096
	ds_write_b128 v130, v[112:115] offset:4624
	ds_write_b128 v130, v[116:119] offset:5152
	ds_write_b128 v130, v[120:123] offset:5680
	v_cvt_pk_bf16_f32 v92, v108, v109
	v_cvt_pk_bf16_f32 v93, v110, v111
	v_cvt_pk_bf16_f32 v94, v112, v113
	v_cvt_pk_bf16_f32 v95, v114, v115
	v_cvt_pk_bf16_f32 v96, v116, v117
	v_cvt_pk_bf16_f32 v97, v118, v119
	v_cvt_pk_bf16_f32 v98, v120, v121
	v_cvt_pk_bf16_f32 v99, v122, v123
	ds_write_b64 v131, v[92:93] offset:37888
	ds_write_b64 v131, v[94:95] offset:38160
	ds_write_b64 v131, v[96:97] offset:38432
	ds_write_b64 v131, v[98:99] offset:38704
	s_waitcnt lgkmcnt(0)
	s_barrier
	ds_read_b128 v[72:75], v192 offset:37888
	ds_read_b128 v[136:139], v192 offset:37952
	s_waitcnt lgkmcnt(1)
	v_mfma_f32_16x16x32_bf16 v[76:79], v[72:75], v[0:3], 0
	ds_read_b128 v[88:91], v192 offset:42240
	ds_read_b128 v[104:107], v192 offset:46592
	ds_read_b128 v[120:123], v192 offset:50944
	v_mfma_f32_16x16x32_bf16 v[80:83], v[72:75], v[20:23], 0
	s_cmp_ge_i32 s0, s1
	v_mfma_f32_16x16x32_bf16 v[84:87], v[72:75], v[36:39], 0
	s_waitcnt vmcnt(5)
	v_mfma_f32_16x16x32_bf16 v[72:75], v[72:75], v[56:59], 0
	s_waitcnt lgkmcnt(3)
	v_mfma_f32_16x16x32_bf16 v[76:79], v[136:139], v[4:7], v[76:79]
	v_mfma_f32_16x16x32_bf16 v[80:83], v[136:139], v[16:19], v[80:83]
	v_mfma_f32_16x16x32_bf16 v[84:87], v[136:139], v[32:35], v[84:87]
	v_mfma_f32_16x16x32_bf16 v[72:75], v[136:139], v[48:51], v[72:75]
	ds_read_b128 v[136:139], v192 offset:42304
	s_waitcnt lgkmcnt(3)
	v_mfma_f32_16x16x32_bf16 v[92:95], v[88:91], v[0:3], 0
	v_mfma_f32_16x16x32_bf16 v[96:99], v[88:91], v[20:23], 0
	v_mfma_f32_16x16x32_bf16 v[100:103], v[88:91], v[36:39], 0
	v_mfma_f32_16x16x32_bf16 v[88:91], v[88:91], v[56:59], 0
	s_waitcnt lgkmcnt(0)
	v_mfma_f32_16x16x32_bf16 v[92:95], v[136:139], v[4:7], v[92:95]
	v_mfma_f32_16x16x32_bf16 v[96:99], v[136:139], v[16:19], v[96:99]
	v_mfma_f32_16x16x32_bf16 v[100:103], v[136:139], v[32:35], v[100:103]
	v_mfma_f32_16x16x32_bf16 v[88:91], v[136:139], v[48:51], v[88:91]
	ds_read_b128 v[136:139], v192 offset:46656
	v_mfma_f32_16x16x32_bf16 v[108:111], v[104:107], v[0:3], 0
	v_mfma_f32_16x16x32_bf16 v[112:115], v[104:107], v[20:23], 0
	v_mfma_f32_16x16x32_bf16 v[116:119], v[104:107], v[36:39], 0
	v_mfma_f32_16x16x32_bf16 v[104:107], v[104:107], v[56:59], 0
	s_waitcnt lgkmcnt(0)
	v_mfma_f32_16x16x32_bf16 v[108:111], v[136:139], v[4:7], v[108:111]
	v_mfma_f32_16x16x32_bf16 v[112:115], v[136:139], v[16:19], v[112:115]
	v_mfma_f32_16x16x32_bf16 v[116:119], v[136:139], v[32:35], v[116:119]
	v_mfma_f32_16x16x32_bf16 v[104:107], v[136:139], v[48:51], v[104:107]
	ds_read_b128 v[136:139], v192 offset:51008
	v_mfma_f32_16x16x32_bf16 v[124:127], v[120:123], v[0:3], 0
	v_mfma_f32_16x16x32_bf16 v[128:131], v[120:123], v[20:23], 0
	v_mfma_f32_16x16x32_bf16 v[132:135], v[120:123], v[36:39], 0
	v_mfma_f32_16x16x32_bf16 v[120:123], v[120:123], v[56:59], 0
	s_waitcnt lgkmcnt(0)
	v_mfma_f32_16x16x32_bf16 v[124:127], v[136:139], v[4:7], v[124:127]
	v_mfma_f32_16x16x32_bf16 v[128:131], v[136:139], v[16:19], v[128:131]
	v_mfma_f32_16x16x32_bf16 v[132:135], v[136:139], v[32:35], v[132:135]
	v_mfma_f32_16x16x32_bf16 v[120:123], v[136:139], v[48:51], v[120:123]
	ds_read_b128 v[136:139], v192 offset:38016
	s_waitcnt lgkmcnt(0)
	v_mfma_f32_16x16x32_bf16 v[76:79], v[136:139], v[8:11], v[76:79]
	v_mfma_f32_16x16x32_bf16 v[80:83], v[136:139], v[24:27], v[80:83]
	v_mfma_f32_16x16x32_bf16 v[84:87], v[136:139], v[40:43], v[84:87]
	v_mfma_f32_16x16x32_bf16 v[136:139], v[136:139], v[52:55], v[72:75]
	s_nop 2
	ds_read_b128 v[72:75], v192 offset:42368
	s_waitcnt lgkmcnt(0)
	v_mfma_f32_16x16x32_bf16 v[92:95], v[72:75], v[8:11], v[92:95]
	v_mfma_f32_16x16x32_bf16 v[96:99], v[72:75], v[24:27], v[96:99]
	v_mfma_f32_16x16x32_bf16 v[100:103], v[72:75], v[40:43], v[100:103]
	v_mfma_f32_16x16x32_bf16 v[88:91], v[72:75], v[52:55], v[88:91]
	ds_read_b128 v[72:75], v192 offset:46720
	s_waitcnt lgkmcnt(0)
	v_mfma_f32_16x16x32_bf16 v[140:143], v[72:75], v[8:11], v[108:111]
	v_mfma_f32_16x16x32_bf16 v[144:147], v[72:75], v[24:27], v[112:115]
	v_mfma_f32_16x16x32_bf16 v[148:151], v[72:75], v[40:43], v[116:119]
	s_nop 1
	ds_read_b128 v[112:115], v192 offset:38080
	v_mfma_f32_16x16x32_bf16 v[206:209], v[72:75], v[52:55], v[104:107]
	ds_read_b128 v[72:75], v192 offset:51072
	s_waitcnt lgkmcnt(0)
	v_mfma_f32_16x16x32_bf16 v[210:213], v[72:75], v[8:11], v[124:127]
	v_mfma_f32_16x16x32_bf16 v[128:131], v[72:75], v[24:27], v[128:131]
	v_mfma_f32_16x16x32_bf16 v[132:135], v[72:75], v[40:43], v[132:135]
	v_mfma_f32_16x16x32_bf16 v[214:217], v[72:75], v[52:55], v[120:123]
	v_mfma_f32_16x16x32_bf16 v[72:75], v[112:115], v[44:47], v[84:87]
	s_nop 2
	ds_read_b128 v[84:87], v192 offset:42432
	v_mfma_f32_16x16x32_bf16 v[104:107], v[112:115], v[12:15], v[76:79]
	s_nop 2
	v_add_f32_e32 v75, v173, v75
	v_exp_f32_e32 v75, v75
	v_add_f32_e32 v74, v173, v74
	v_mfma_f32_16x16x32_bf16 v[108:111], v[112:115], v[28:31], v[80:83]
	v_exp_f32_e32 v74, v74
	v_add_f32_e32 v107, v172, v107
	v_exp_f32_e32 v107, v107
	s_waitcnt vmcnt(4)
	v_mfma_f32_16x16x32_bf16 v[76:79], v[112:115], v[60:63], v[136:139]
	v_add_f32_e32 v106, v172, v106
	v_exp_f32_e32 v106, v106
	v_add_f32_e32 v107, 1.0, v107
	s_waitcnt lgkmcnt(0)
	v_mfma_f32_16x16x32_bf16 v[112:115], v[84:87], v[12:15], v[92:95]
	v_rcp_f32_e32 v107, v107
	v_add_f32_e32 v111, v174, v111
	v_add_f32_e32 v106, 1.0, v106
	v_mfma_f32_16x16x32_bf16 v[80:83], v[84:87], v[44:47], v[100:103]
	ds_read_b128 v[92:95], v192 offset:46784
	s_nop 2
	v_add_f32_e32 v115, v172, v115
	v_exp_f32_e32 v115, v115
	ds_read_b128 v[100:103], v192 offset:51136
	v_mfma_f32_16x16x32_bf16 v[116:119], v[84:87], v[28:31], v[96:99]
	v_add_f32_e32 v114, v172, v114
	v_add_f32_e32 v115, 1.0, v115
	v_rcp_f32_e32 v115, v115
	v_mfma_f32_16x16x32_bf16 v[84:87], v[84:87], v[60:63], v[88:91]
	v_exp_f32_e32 v114, v114
	s_nop 2
	v_add_f32_e32 v119, v174, v119
	v_mul_f32_e32 v115, v176, v115
	s_waitcnt lgkmcnt(1)
	v_mfma_f32_16x16x32_bf16 v[88:91], v[92:95], v[44:47], v[148:151]
	v_exp_f32_e32 v115, v115
	v_add_f32_e32 v114, 1.0, v114
	v_exp_f32_e32 v119, v119
	s_waitcnt lgkmcnt(0)
	v_mfma_f32_16x16x32_bf16 v[148:151], v[100:103], v[12:15], v[210:213]
	v_rcp_f32_e32 v114, v114
	v_add_f32_e32 v113, v172, v113
	v_exp_f32_e32 v113, v113
	v_mfma_f32_16x16x32_bf16 v[124:127], v[92:95], v[28:31], v[144:147]
	v_add_f32_e32 v119, 1.0, v119
	s_nop 2
	v_add_f32_e32 v148, v172, v148
	v_exp_f32_e32 v148, v148
	v_add_f32_e32 v145, v172, v151
	v_exp_f32_e32 v145, v145
	v_mfma_f32_16x16x32_bf16 v[120:123], v[92:95], v[12:15], v[140:143]
	v_add_f32_e32 v146, v172, v150
	v_exp_f32_e32 v146, v146
	v_add_f32_e32 v145, 1.0, v145
	v_rcp_f32_e32 v145, v145
	v_mfma_f32_16x16x32_bf16 v[92:95], v[92:95], v[60:63], v[206:209]
	v_add_f32_e32 v146, 1.0, v146
	v_rcp_f32_e32 v146, v146
	v_mul_f32_e32 v145, v176, v145
	v_mfma_f32_16x16x32_bf16 v[206:209], v[100:103], v[28:31], v[128:131]
	v_exp_f32_e32 v151, v145
	v_mul_f32_e32 v146, v176, v146
	v_add_f32_e32 v147, v172, v149
	v_exp_f32_e32 v150, v146
	v_fma_f32 v145, -v151, v151, 1.0
	s_nop 2
	v_add_f32_e32 v144, v174, v209
	v_exp_f32_e32 v144, v144
	v_max_f32_e32 v145, 0, v145
	v_sqrt_f32_e32 v145, v145
	v_exp_f32_e32 v147, v147
	v_add_f32_e32 v144, 1.0, v144
	v_rcp_f32_e32 v144, v144
	v_fma_f32 v146, -v150, v150, 1.0
	v_add_f32_e32 v147, 1.0, v147
	v_max_f32_e32 v146, 0, v146
	v_mul_f32_e32 v144, v144, v145
	v_add_f32_e32 v145, v174, v208
	v_exp_f32_e32 v145, v145
	v_rcp_f32_e32 v147, v147
	v_sqrt_f32_e32 v146, v146
	v_add_f32_e32 v148, 1.0, v148
	v_add_f32_e32 v145, 1.0, v145
	v_rcp_f32_e32 v145, v145
	v_mul_f32_e32 v147, v176, v147
	v_exp_f32_e32 v149, v147
	v_rcp_f32_e32 v148, v148
	v_mul_f32_e32 v145, v145, v146
	v_add_f32_e32 v146, v174, v207
	v_exp_f32_e32 v146, v146
	v_fma_f32 v147, -v149, v149, 1.0
	v_max_f32_e32 v147, 0, v147
	v_sqrt_f32_e32 v147, v147
	v_add_f32_e32 v146, 1.0, v146
	v_rcp_f32_e32 v146, v146
	v_mul_f32_e32 v148, v176, v148
	v_add_f32_e32 v123, v172, v123
	v_exp_f32_e32 v148, v148
	v_mul_f32_e32 v146, v146, v147
	v_add_f32_e32 v147, v174, v206
	v_exp_f32_e32 v123, v123
	v_exp_f32_e32 v147, v147
	v_fma_f32 v152, -v148, v148, 1.0
	v_max_f32_e32 v152, 0, v152
	v_add_f32_e32 v123, 1.0, v123
	v_add_f32_e32 v147, 1.0, v147
	v_rcp_f32_e32 v123, v123
	v_rcp_f32_e32 v147, v147
	v_sqrt_f32_e32 v152, v152
	v_add_f32_e32 v122, v172, v122
	v_mul_f32_e32 v123, v176, v123
	v_add_f32_e32 v127, v174, v127
	v_mul_f32_e32 v147, v147, v152
	v_exp_f32_e32 v152, v123
	v_exp_f32_e32 v122, v122
	v_exp_f32_e32 v127, v127
	v_add_f32_e32 v121, v172, v121
	v_fma_f32 v123, -v152, v152, 1.0
	v_add_f32_e32 v122, 1.0, v122
	v_add_f32_e32 v127, 1.0, v127
	v_max_f32_e32 v123, 0, v123
	v_rcp_f32_e32 v122, v122
	v_rcp_f32_e32 v127, v127
	v_sqrt_f32_e32 v123, v123
	v_exp_f32_e32 v121, v121
	v_mul_f32_e32 v122, v176, v122
	v_add_f32_e32 v126, v174, v126
	v_mul_f32_e32 v123, v127, v123
	v_exp_f32_e32 v127, v122
	v_add_f32_e32 v121, 1.0, v121
	v_exp_f32_e32 v126, v126
	v_rcp_f32_e32 v121, v121
	v_add_f32_e32 v120, v172, v120
	v_exp_f32_e32 v120, v120
	v_fma_f32 v122, -v127, v127, 1.0
	v_add_f32_e32 v126, 1.0, v126
	v_max_f32_e32 v122, 0, v122
	v_mul_f32_e32 v121, v176, v121
	v_rcp_f32_e32 v126, v126
	v_sqrt_f32_e32 v122, v122
	v_add_f32_e32 v125, v174, v125
	v_exp_f32_e32 v121, v121
	v_add_f32_e32 v120, 1.0, v120
	v_exp_f32_e32 v125, v125
	v_rcp_f32_e32 v120, v120
	v_mul_f32_e32 v122, v126, v122
	v_fma_f32 v126, -v121, v121, 1.0
	v_add_f32_e32 v125, 1.0, v125
	v_max_f32_e32 v126, 0, v126
	v_mul_f32_e32 v120, v176, v120
	v_rcp_f32_e32 v125, v125
	v_sqrt_f32_e32 v126, v126
	v_add_f32_e32 v124, v174, v124
	v_exp_f32_e32 v120, v120
	v_exp_f32_e32 v124, v124
	v_mul_f32_e32 v125, v125, v126
	v_mul_f32_e32 v114, v176, v114
	v_fma_f32 v126, -v120, v120, 1.0
	v_add_f32_e32 v124, 1.0, v124
	v_max_f32_e32 v126, 0, v126
	v_rcp_f32_e32 v124, v124
	v_sqrt_f32_e32 v126, v126
	v_rcp_f32_e32 v119, v119
	v_add_f32_e32 v118, v174, v118
	v_exp_f32_e32 v114, v114
	v_mul_f32_e32 v124, v124, v126
	v_fma_f32 v126, -v115, v115, 1.0
	v_max_f32_e32 v126, 0, v126
	v_sqrt_f32_e32 v126, v126
	v_add_f32_e32 v113, 1.0, v113
	v_exp_f32_e32 v118, v118
	v_rcp_f32_e32 v113, v113
	v_add_f32_e32 v112, v172, v112
	v_exp_f32_e32 v112, v112
	v_mul_f32_e32 v119, v119, v126
	v_fma_f32 v126, -v114, v114, 1.0
	v_add_f32_e32 v118, 1.0, v118
	v_max_f32_e32 v126, 0, v126
	v_mul_f32_e32 v113, v176, v113
	v_rcp_f32_e32 v118, v118
	v_sqrt_f32_e32 v126, v126
	v_add_f32_e32 v117, v174, v117
	v_exp_f32_e32 v113, v113
	v_add_f32_e32 v112, 1.0, v112
	v_exp_f32_e32 v117, v117
	v_rcp_f32_e32 v112, v112
	v_mul_f32_e32 v118, v118, v126
	v_fma_f32 v126, -v113, v113, 1.0
	v_add_f32_e32 v117, 1.0, v117
	v_max_f32_e32 v126, 0, v126
	v_mul_f32_e32 v112, v176, v112
	v_rcp_f32_e32 v117, v117
	v_sqrt_f32_e32 v126, v126
	v_add_f32_e32 v116, v174, v116
	v_exp_f32_e32 v112, v112
	v_exp_f32_e32 v116, v116
	v_mul_f32_e32 v117, v117, v126
	v_mul_f32_e32 v107, v176, v107
	v_fma_f32 v126, -v112, v112, 1.0
	v_add_f32_e32 v116, 1.0, v116
	v_max_f32_e32 v126, 0, v126
	v_rcp_f32_e32 v116, v116
	v_sqrt_f32_e32 v126, v126
	v_exp_f32_e32 v107, v107
	v_exp_f32_e32 v111, v111
	v_rcp_f32_e32 v106, v106
	v_add_f32_e32 v105, v172, v105
	v_exp_f32_e32 v105, v105
	v_mul_f32_e32 v116, v116, v126
	v_fma_f32 v126, -v107, v107, 1.0
	v_add_f32_e32 v111, 1.0, v111
	v_max_f32_e32 v126, 0, v126
	v_mul_f32_e32 v106, v176, v106
	v_rcp_f32_e32 v111, v111
	v_sqrt_f32_e32 v126, v126
	v_add_f32_e32 v110, v174, v110
	v_exp_f32_e32 v106, v106
	v_add_f32_e32 v105, 1.0, v105
	v_exp_f32_e32 v110, v110
	v_rcp_f32_e32 v105, v105
	v_add_f32_e32 v104, v172, v104
	v_exp_f32_e32 v104, v104
	v_mul_f32_e32 v111, v111, v126
	v_fma_f32 v126, -v106, v106, 1.0
	v_add_f32_e32 v110, 1.0, v110
	v_max_f32_e32 v126, 0, v126
	v_mul_f32_e32 v105, v176, v105
	v_rcp_f32_e32 v110, v110
	v_sqrt_f32_e32 v126, v126
	v_add_f32_e32 v109, v174, v109
	v_exp_f32_e32 v105, v105
	v_add_f32_e32 v104, 1.0, v104
	v_exp_f32_e32 v109, v109
	v_rcp_f32_e32 v104, v104
	v_mul_f32_e32 v110, v110, v126
	v_fma_f32 v126, -v105, v105, 1.0
	v_add_f32_e32 v109, 1.0, v109
	v_max_f32_e32 v126, 0, v126
	v_mul_f32_e32 v104, v176, v104
	v_rcp_f32_e32 v109, v109
	v_sqrt_f32_e32 v126, v126
	v_add_f32_e32 v108, v174, v108
	v_exp_f32_e32 v104, v104
	v_exp_f32_e32 v108, v108
	v_mul_f32_e32 v109, v109, v126
	v_add_u32_e32 v128, 0x1000, v193
	v_fma_f32 v126, -v104, v104, 1.0
	v_add_f32_e32 v108, 1.0, v108
	v_max_f32_e32 v126, 0, v126
	ds_read2_b32 v[128:129], v128 offset1:132
	v_rcp_f32_e32 v108, v108
	v_sqrt_f32_e32 v126, v126
	v_add_u32_e32 v130, 0x1400, v193
	ds_read2_b32 v[130:131], v130 offset0:8 offset1:140
	v_mfma_f32_16x16x32_bf16 v[96:99], v[100:103], v[44:47], v[132:135]
	v_mul_f32_e32 v108, v108, v126
	s_waitcnt lgkmcnt(1)
	v_mul_f32_e32 v108, v108, v128
	v_mul_f32_e32 v109, v109, v129
	v_add_u32_e32 v132, 0x3000, v193
	ds_read2_b32 v[132:133], v132 offset0:64 offset1:196
	v_add_u32_e32 v134, 0x3400, v193
	ds_read2_b32 v[134:135], v134 offset0:72 offset1:204
	v_fma_f32 v126, 0, v104, v108
	v_add_u32_e32 v136, 0x5200, v193
	s_waitcnt lgkmcnt(2)
	v_mul_f32_e32 v110, v110, v130
	v_fma_f32 v126, v105, v126, v109
	v_mul_f32_e32 v153, v104, v105
	ds_read2_b32 v[136:137], v136 offset1:132
	v_mul_f32_e32 v111, v111, v131
	v_fma_f32 v126, v106, v126, v110
	v_mul_f32_e32 v153, v106, v153
	v_add_u32_e32 v138, 0x5600, v193
	s_waitcnt lgkmcnt(2)
	v_mul_f32_e32 v116, v116, v132
	v_fma_f32 v126, v107, v126, v111
	v_mul_f32_e32 v153, v107, v153
	ds_read2_b32 v[138:139], v138 offset0:8 offset1:140
	v_mul_f32_e32 v117, v117, v133
	v_fma_f32 v126, v112, v126, v116
	v_mul_f32_e32 v153, v153, v112
	v_add_u32_e32 v140, 0x7200, v193
	s_waitcnt lgkmcnt(2)
	v_mul_f32_e32 v118, v118, v134
	v_fma_f32 v126, v113, v126, v117
	v_mul_f32_e32 v153, v113, v153
	ds_read2_b32 v[140:141], v140 offset0:64 offset1:196
	v_mul_f32_e32 v119, v119, v135
	v_fma_f32 v126, v114, v126, v118
	v_mul_f32_e32 v153, v114, v153
	v_add_u32_e32 v142, 0x7600, v193
	s_waitcnt lgkmcnt(2)
	v_mul_f32_e32 v124, v124, v136
	v_fma_f32 v126, v115, v126, v119
	v_mul_f32_e32 v153, v115, v153
	ds_read2_b32 v[142:143], v142 offset0:72 offset1:204
	v_mul_f32_e32 v125, v125, v137
	v_fma_f32 v126, v120, v126, v124
	v_mul_f32_e32 v153, v153, v120
	s_waitcnt lgkmcnt(2)
	v_mul_f32_e32 v122, v122, v138
	v_fma_f32 v126, v121, v126, v125
	v_mul_f32_e32 v153, v121, v153
	v_mul_f32_e32 v123, v123, v139
	v_fma_f32 v126, v127, v126, v122
	v_mul_f32_e32 v153, v127, v153
	v_add_f32_e32 v99, v173, v99
	s_waitcnt lgkmcnt(1)
	v_mul_f32_e32 v147, v147, v140
	v_fma_f32 v126, v152, v126, v123
	v_mul_f32_e32 v153, v152, v153
	v_exp_f32_e32 v99, v99
	v_mul_f32_e32 v146, v146, v141
	v_fma_f32 v126, v148, v126, v147
	v_mul_f32_e32 v153, v153, v148
	s_waitcnt lgkmcnt(0)
	v_mul_f32_e32 v145, v145, v142
	v_fma_f32 v126, v149, v126, v146
	v_mul_f32_e32 v153, v149, v153
	v_mul_f32_e32 v144, v144, v143
	v_fma_f32 v126, v150, v126, v145
	v_mul_f32_e32 v153, v150, v153
	v_fma_f32 v126, v151, v126, v144
	v_mul_f32_e32 v153, v151, v153
	v_add_f32_e32 v99, 1.0, v99
	ds_bpermute_b32 v205, v196, v153
	ds_bpermute_b32 v207, v196, v126
	v_rcp_f32_e32 v99, v99
	v_add_f32_e32 v98, v173, v98
	v_mfma_f32_16x16x32_bf16 v[100:103], v[100:103], v[60:63], v[214:217]
	ds_bpermute_b32 v206, v199, v153
	ds_bpermute_b32 v208, v199, v126
	v_exp_f32_e32 v98, v98
	ds_bpermute_b32 v153, v200, v153
	ds_bpermute_b32 v126, v200, v126
	v_mul_f32_e32 v99, v177, v99
	s_waitcnt vmcnt(3) lgkmcnt(4)
	v_fmac_f32_e32 v207, v204, v205
	v_add_f32_e32 v103, v175, v103
	v_exp_f32_e32 v99, v99
	v_add_f32_e32 v98, 1.0, v98
	v_cndmask_b32_e64 v204, v204, v207, s[6:7]
	s_waitcnt lgkmcnt(2)
	v_fmac_f32_e32 v208, v207, v206
	v_exp_f32_e32 v103, v103
	v_rcp_f32_e32 v98, v98
	v_add_f32_e32 v97, v173, v97
	v_cndmask_b32_e64 v204, v204, v208, s[4:5]
	s_waitcnt lgkmcnt(0)
	v_fmac_f32_e32 v126, v208, v153
	v_exp_f32_e32 v97, v97
	v_cndmask_b32_e64 v126, v204, v126, s[10:11]
	v_fmac_f32_e32 v108, v104, v126
	v_fma_f32 v104, -v99, v99, 1.0
	v_add_f32_e32 v103, 1.0, v103
	v_max_f32_e32 v104, 0, v104
	v_mul_f32_e32 v98, v177, v98
	v_rcp_f32_e32 v103, v103
	v_sqrt_f32_e32 v104, v104
	v_add_f32_e32 v102, v175, v102
	v_exp_f32_e32 v98, v98
	v_add_f32_e32 v97, 1.0, v97
	v_exp_f32_e32 v102, v102
	v_rcp_f32_e32 v97, v97
	v_add_f32_e32 v96, v173, v96
	v_exp_f32_e32 v96, v96
	v_mul_f32_e32 v103, v103, v104
	v_fma_f32 v104, -v98, v98, 1.0
	v_add_f32_e32 v102, 1.0, v102
	v_max_f32_e32 v104, 0, v104
	v_mul_f32_e32 v97, v177, v97
	v_rcp_f32_e32 v102, v102
	v_sqrt_f32_e32 v104, v104
	v_add_f32_e32 v101, v175, v101
	v_exp_f32_e32 v97, v97
	v_add_f32_e32 v96, 1.0, v96
	v_exp_f32_e32 v101, v101
	v_rcp_f32_e32 v96, v96
	v_add_f32_e32 v91, v173, v91
	v_exp_f32_e32 v91, v91
	v_mul_f32_e32 v102, v102, v104
	v_fma_f32 v104, -v97, v97, 1.0
	v_add_f32_e32 v101, 1.0, v101
	v_max_f32_e32 v104, 0, v104
	v_mul_f32_e32 v96, v177, v96
	v_rcp_f32_e32 v101, v101
	v_sqrt_f32_e32 v104, v104
	v_add_f32_e32 v100, v175, v100
	v_exp_f32_e32 v96, v96
	v_add_f32_e32 v91, 1.0, v91
	v_exp_f32_e32 v100, v100
	v_rcp_f32_e32 v91, v91
	v_add_f32_e32 v90, v173, v90
	v_exp_f32_e32 v90, v90
	v_mul_f32_e32 v101, v101, v104
	v_fma_f32 v104, -v96, v96, 1.0
	v_add_f32_e32 v100, 1.0, v100
	v_max_f32_e32 v104, 0, v104
	v_mul_f32_e32 v91, v177, v91
	v_rcp_f32_e32 v100, v100
	v_sqrt_f32_e32 v104, v104
	v_add_f32_e32 v95, v175, v95
	v_exp_f32_e32 v91, v91
	v_add_f32_e32 v90, 1.0, v90
	v_exp_f32_e32 v95, v95
	v_rcp_f32_e32 v90, v90
	v_add_f32_e32 v89, v173, v89
	v_exp_f32_e32 v89, v89
	v_mul_f32_e32 v100, v100, v104
	v_fma_f32 v104, -v91, v91, 1.0
	v_add_f32_e32 v95, 1.0, v95
	v_max_f32_e32 v104, 0, v104
	v_mul_f32_e32 v90, v177, v90
	v_rcp_f32_e32 v95, v95
	v_sqrt_f32_e32 v104, v104
	v_add_f32_e32 v94, v175, v94
	v_exp_f32_e32 v90, v90
	v_add_f32_e32 v89, 1.0, v89
	v_exp_f32_e32 v94, v94
	v_rcp_f32_e32 v89, v89
	v_add_f32_e32 v88, v173, v88
	v_exp_f32_e32 v88, v88
	v_mul_f32_e32 v95, v95, v104
	v_fma_f32 v104, -v90, v90, 1.0
	v_add_f32_e32 v94, 1.0, v94
	v_max_f32_e32 v104, 0, v104
	v_mul_f32_e32 v89, v177, v89
	v_rcp_f32_e32 v94, v94
	v_sqrt_f32_e32 v104, v104
	v_add_f32_e32 v93, v175, v93
	v_exp_f32_e32 v89, v89
	v_add_f32_e32 v88, 1.0, v88
	v_exp_f32_e32 v93, v93
	v_rcp_f32_e32 v88, v88
	v_add_f32_e32 v83, v173, v83
	v_exp_f32_e32 v83, v83
	v_mul_f32_e32 v94, v94, v104
	v_fma_f32 v104, -v89, v89, 1.0
	v_add_f32_e32 v93, 1.0, v93
	v_max_f32_e32 v104, 0, v104
	v_mul_f32_e32 v88, v177, v88
	v_rcp_f32_e32 v93, v93
	v_sqrt_f32_e32 v104, v104
	v_add_f32_e32 v92, v175, v92
	v_exp_f32_e32 v88, v88
	v_add_f32_e32 v83, 1.0, v83
	v_exp_f32_e32 v92, v92
	v_rcp_f32_e32 v83, v83
	v_add_f32_e32 v82, v173, v82
	v_exp_f32_e32 v82, v82
	v_mul_f32_e32 v93, v93, v104
	v_fma_f32 v104, -v88, v88, 1.0
	v_add_f32_e32 v92, 1.0, v92
	v_max_f32_e32 v104, 0, v104
	v_mul_f32_e32 v83, v177, v83
	v_rcp_f32_e32 v92, v92
	v_sqrt_f32_e32 v104, v104
	v_add_f32_e32 v87, v175, v87
	v_exp_f32_e32 v83, v83
	v_add_f32_e32 v82, 1.0, v82
	v_exp_f32_e32 v87, v87
	v_rcp_f32_e32 v82, v82
	v_add_f32_e32 v81, v173, v81
	v_exp_f32_e32 v81, v81
	v_mul_f32_e32 v92, v92, v104
	v_fma_f32 v104, -v83, v83, 1.0
	v_add_f32_e32 v87, 1.0, v87
	v_max_f32_e32 v104, 0, v104
	v_mul_f32_e32 v82, v177, v82
	v_rcp_f32_e32 v87, v87
	v_sqrt_f32_e32 v104, v104
	v_add_f32_e32 v86, v175, v86
	v_exp_f32_e32 v82, v82
	v_add_f32_e32 v81, 1.0, v81
	v_exp_f32_e32 v86, v86
	v_rcp_f32_e32 v81, v81
	v_add_f32_e32 v80, v173, v80
	v_exp_f32_e32 v80, v80
	v_mul_f32_e32 v87, v87, v104
	v_fma_f32 v104, -v82, v82, 1.0
	v_add_f32_e32 v86, 1.0, v86
	v_max_f32_e32 v104, 0, v104
	v_mul_f32_e32 v81, v177, v81
	v_rcp_f32_e32 v86, v86
	v_sqrt_f32_e32 v104, v104
	v_add_f32_e32 v85, v175, v85
	v_exp_f32_e32 v81, v81
	v_exp_f32_e32 v85, v85
	v_add_f32_e32 v80, 1.0, v80
	v_rcp_f32_e32 v80, v80
	v_mul_f32_e32 v86, v86, v104
	v_fma_f32 v104, -v81, v81, 1.0
	v_add_f32_e32 v85, 1.0, v85
	v_max_f32_e32 v104, 0, v104
	v_rcp_f32_e32 v85, v85
	v_sqrt_f32_e32 v104, v104
	v_mul_f32_e32 v80, v177, v80
	v_add_f32_e32 v84, v175, v84
	v_exp_f32_e32 v80, v80
	v_exp_f32_e32 v84, v84
	v_add_f32_e32 v75, 1.0, v75
	v_rcp_f32_e32 v75, v75
	v_mul_f32_e32 v85, v85, v104
	v_mul_f32_e32 v104, v85, v133
	v_fma_f32 v85, -v80, v80, 1.0
	v_add_f32_e32 v84, 1.0, v84
	v_max_f32_e32 v85, 0, v85
	v_rcp_f32_e32 v84, v84
	v_sqrt_f32_e32 v85, v85
	v_mul_f32_e32 v75, v177, v75
	v_add_f32_e32 v79, v175, v79
	v_exp_f32_e32 v75, v75
	v_add_f32_e32 v74, 1.0, v74
	v_exp_f32_e32 v79, v79
	v_rcp_f32_e32 v74, v74
	v_add_f32_e32 v73, v173, v73
	v_exp_f32_e32 v73, v73
	v_mul_f32_e32 v84, v84, v85
	v_fmac_f32_e32 v109, v105, v108
	v_mul_f32_e32 v105, v84, v132
	v_fma_f32 v84, -v75, v75, 1.0
	v_add_f32_e32 v79, 1.0, v79
	v_max_f32_e32 v84, 0, v84
	v_mul_f32_e32 v74, v177, v74
	v_rcp_f32_e32 v79, v79
	v_sqrt_f32_e32 v84, v84
	v_add_f32_e32 v78, v175, v78
	v_exp_f32_e32 v74, v74
	v_add_f32_e32 v73, 1.0, v73
	v_exp_f32_e32 v78, v78
	v_rcp_f32_e32 v73, v73
	v_add_f32_e32 v72, v173, v72
	v_exp_f32_e32 v72, v72
	v_mul_f32_e32 v79, v79, v84
	v_fma_f32 v84, -v74, v74, 1.0
	v_add_f32_e32 v78, 1.0, v78
	v_max_f32_e32 v84, 0, v84
	v_mul_f32_e32 v73, v177, v73
	v_rcp_f32_e32 v78, v78
	v_sqrt_f32_e32 v84, v84
	v_add_f32_e32 v77, v175, v77
	v_exp_f32_e32 v73, v73
	v_add_f32_e32 v72, 1.0, v72
	v_exp_f32_e32 v77, v77
	v_rcp_f32_e32 v72, v72
	v_mul_f32_e32 v78, v78, v84
	v_fma_f32 v84, -v73, v73, 1.0
	v_add_f32_e32 v77, 1.0, v77
	v_max_f32_e32 v84, 0, v84
	v_mul_f32_e32 v72, v177, v72
	v_rcp_f32_e32 v77, v77
	v_sqrt_f32_e32 v84, v84
	v_add_f32_e32 v76, v175, v76
	v_exp_f32_e32 v72, v72
	v_exp_f32_e32 v76, v76
	v_mul_f32_e32 v77, v77, v84
	v_mul_f32_e32 v103, v103, v143
	v_fma_f32 v84, -v72, v72, 1.0
	v_add_f32_e32 v76, 1.0, v76
	v_max_f32_e32 v84, 0, v84
	v_rcp_f32_e32 v76, v76
	v_sqrt_f32_e32 v84, v84
	v_mul_f32_e32 v102, v102, v142
	v_mul_f32_e32 v101, v101, v141
	v_mul_f32_e32 v85, v99, v98
	v_mul_f32_e32 v76, v76, v84
	v_fma_f32 v84, 0, v99, v103
	v_fma_f32 v84, v98, v84, v102
	v_mul_f32_e32 v100, v100, v140
	v_fma_f32 v84, v97, v84, v101
	v_mul_f32_e32 v85, v97, v85
	v_mul_f32_e32 v95, v95, v139
	v_fma_f32 v84, v96, v84, v100
	v_mul_f32_e32 v85, v96, v85
	v_mul_f32_e32 v94, v94, v138
	v_fma_f32 v84, v91, v84, v95
	v_mul_f32_e32 v85, v91, v85
	v_mul_f32_e32 v93, v93, v137
	v_fma_f32 v84, v90, v84, v94
	v_mul_f32_e32 v85, v90, v85
	v_mul_f32_e32 v92, v92, v136
	v_fma_f32 v84, v89, v84, v93
	v_mul_f32_e32 v85, v89, v85
	v_mul_f32_e32 v87, v87, v135
	v_fma_f32 v84, v88, v84, v92
	v_mul_f32_e32 v85, v88, v85
	v_mul_f32_e32 v86, v86, v134
	v_fma_f32 v84, v83, v84, v87
	v_mul_f32_e32 v85, v83, v85
	v_fma_f32 v84, v82, v84, v86
	v_mul_f32_e32 v85, v82, v85
	v_fma_f32 v84, v81, v84, v104
	v_mul_f32_e32 v85, v81, v85
	v_mul_f32_e32 v79, v79, v131
	v_fma_f32 v84, v80, v84, v105
	v_mul_f32_e32 v85, v80, v85
	v_mul_f32_e32 v78, v78, v130
	v_fma_f32 v84, v75, v84, v79
	v_mul_f32_e32 v85, v75, v85
	v_fmac_f32_e32 v110, v106, v109
	v_mul_f32_e32 v77, v77, v129
	v_fma_f32 v84, v74, v84, v78
	v_mul_f32_e32 v85, v74, v85
	v_fmac_f32_e32 v111, v107, v110
	v_mul_f32_e32 v76, v76, v128
	v_fma_f32 v84, v73, v84, v77
	v_mul_f32_e32 v85, v73, v85
	v_fmac_f32_e32 v116, v112, v111
	v_fma_f32 v84, v72, v84, v76
	v_mul_f32_e32 v85, v72, v85
	v_fmac_f32_e32 v117, v113, v116
	ds_bpermute_b32 v106, v199, v85
	ds_bpermute_b32 v107, v200, v85
	ds_bpermute_b32 v85, v201, v85
	ds_bpermute_b32 v112, v199, v84
	ds_bpermute_b32 v113, v200, v84
	ds_bpermute_b32 v84, v201, v84
	v_fmac_f32_e32 v118, v114, v117
	v_fmac_f32_e32 v119, v115, v118
	v_fmac_f32_e32 v124, v120, v119
	v_fmac_f32_e32 v125, v121, v124
	s_waitcnt vmcnt(2) lgkmcnt(0)
	v_fmac_f32_e32 v84, v203, v85
	v_cndmask_b32_e64 v85, v203, v84, s[4:5]
	v_fmac_f32_e32 v113, v84, v107
	v_cndmask_b32_e64 v84, v85, v113, s[6:7]
	v_fmac_f32_e32 v112, v113, v106
	v_cndmask_b32_e64 v84, v84, v112, s[8:9]
	v_fmac_f32_e32 v103, v99, v84
	v_fmac_f32_e32 v102, v98, v103
	v_fmac_f32_e32 v101, v97, v102
	v_fmac_f32_e32 v100, v96, v101
	v_fmac_f32_e32 v95, v91, v100
	v_fmac_f32_e32 v94, v90, v95
	v_fmac_f32_e32 v93, v89, v94
	v_fmac_f32_e32 v92, v88, v93
	v_fmac_f32_e32 v87, v83, v92
	v_fmac_f32_e32 v86, v82, v87
	v_fmac_f32_e32 v104, v81, v86
	v_fmac_f32_e32 v105, v80, v104
	v_fmac_f32_e32 v79, v75, v105
	v_fmac_f32_e32 v78, v74, v79
	v_fmac_f32_e32 v77, v73, v78
	v_fmac_f32_e32 v76, v72, v77
	v_add_f32_e32 v88, v108, v76
	v_add_f32_e32 v89, v109, v77
	ds_write2_b32 v194, v88, v89 offset1:132
	s_waitcnt vmcnt(1)
	v_lshlrev_b32_e32 v88, 16, v68
	v_and_b32_e32 v89, 0xffff0000, v68
	v_mul_f32_e32 v68, 0xbfb8aa3b, v88
	v_exp_f32_e32 v68, v68
	v_fmac_f32_e32 v122, v127, v125
	v_add_f32_e32 v84, v110, v78
	v_add_f32_e32 v85, v111, v79
	v_add_f32_e32 v68, 1.0, v68
	v_rcp_f32_e32 v90, v68
	v_mul_f32_e32 v68, 0xbfb8aa3b, v89
	v_exp_f32_e32 v68, v68
	v_add_f32_e32 v80, v118, v86
	v_add_u32_e32 v86, 0x400, v194
	v_fmac_f32_e32 v123, v152, v122
	v_add_f32_e32 v82, v116, v105
	v_add_f32_e32 v83, v117, v104
	ds_write2_b32 v86, v84, v85 offset0:8 offset1:140
	v_add_u32_e32 v84, 0x2000, v194
	v_fmac_f32_e32 v147, v148, v123
	v_add_f32_e32 v81, v119, v87
	ds_write2_b32 v84, v82, v83 offset0:64 offset1:196
	v_add_u32_e32 v82, 0x2400, v194
	v_fmac_f32_e32 v146, v149, v147
	v_add_f32_e32 v78, v124, v92
	v_add_f32_e32 v79, v125, v93
	ds_write2_b32 v82, v80, v81 offset0:72 offset1:204
	v_add_u32_e32 v80, 0x4200, v194
	v_add_f32_e32 v68, 1.0, v68
	v_fmac_f32_e32 v145, v150, v146
	v_add_f32_e32 v76, v94, v122
	v_add_f32_e32 v77, v95, v123
	ds_write2_b32 v80, v78, v79 offset1:132
	v_add_u32_e32 v78, 0x4600, v194
	v_rcp_f32_e32 v91, v68
	v_fmac_f32_e32 v144, v151, v145
	v_add_f32_e32 v74, v100, v147
	v_add_f32_e32 v75, v101, v146
	ds_write2_b32 v78, v76, v77 offset0:8 offset1:140
	v_add_u32_e32 v76, 0x6200, v194
	v_add_f32_e32 v72, v102, v145
	v_add_f32_e32 v73, v103, v144
	ds_write2_b32 v76, v74, v75 offset0:64 offset1:196
	v_add_u32_e32 v74, 0x6600, v194
	ds_write2_b32 v74, v72, v73 offset0:72 offset1:204
	s_waitcnt lgkmcnt(0)
	s_barrier
	ds_read_b128 v[72:75], v186
	ds_read_b128 v[76:79], v186 offset:16
	ds_read_b128 v[80:83], v186 offset:32
	ds_read_b128 v[84:87], v186 offset:48
	v_mul_f32_e64 v88, v90, v88
	v_mul_f32_e64 v89, v91, v89
	s_waitcnt lgkmcnt(3)
	v_mul_f32_e64 v72, v88, v72
	v_mul_f32_e64 v73, v89, v73
	s_nop 0
	v_cvt_pk_bf16_f32 v68, v72, v73
	s_waitcnt vmcnt(0)
	v_lshlrev_b32_e32 v72, 16, v64
	v_and_b32_e32 v73, 0xffff0000, v64
	v_mul_f32_e32 v64, 0xbfb8aa3b, v72
	v_exp_f32_e32 v64, v64
	s_nop 0
	v_add_f32_e32 v64, 1.0, v64
	v_rcp_f32_e32 v88, v64
	v_mul_f32_e32 v64, 0xbfb8aa3b, v73
	v_exp_f32_e32 v64, v64
	s_nop 0
	v_add_f32_e32 v64, 1.0, v64
	v_rcp_f32_e32 v89, v64
	s_nop 0
	v_mul_f32_e64 v72, v88, v72
	v_mul_f32_e64 v73, v89, v73
	s_waitcnt lgkmcnt(1)
	v_mul_f32_e64 v72, v72, v80
	v_mul_f32_e64 v73, v73, v81
	s_nop 0
	v_cvt_pk_bf16_f32 v64, v72, v73
	v_lshlrev_b32_e32 v72, 16, v69
	v_and_b32_e32 v73, 0xffff0000, v69
	v_mul_f32_e32 v69, 0xbfb8aa3b, v72
	v_exp_f32_e32 v69, v69
	s_nop 0
	v_add_f32_e32 v69, 1.0, v69
	v_rcp_f32_e32 v80, v69
	v_mul_f32_e32 v69, 0xbfb8aa3b, v73
	v_exp_f32_e32 v69, v69
	s_nop 0
	v_add_f32_e32 v69, 1.0, v69
	v_rcp_f32_e32 v81, v69
	s_nop 0
	v_mul_f32_e64 v72, v80, v72
	v_mul_f32_e64 v73, v81, v73
	s_nop 0
	v_mul_f32_e64 v72, v72, v74
	v_mul_f32_e64 v73, v73, v75
	s_nop 0
	v_cvt_pk_bf16_f32 v69, v72, v73
	v_lshlrev_b32_e32 v72, 16, v65
	v_and_b32_e32 v73, 0xffff0000, v65
	v_mul_f32_e32 v65, 0xbfb8aa3b, v72
	v_exp_f32_e32 v65, v65
	s_nop 0
	v_add_f32_e32 v65, 1.0, v65
	v_rcp_f32_e32 v74, v65
	v_mul_f32_e32 v65, 0xbfb8aa3b, v73
	v_exp_f32_e32 v65, v65
	s_nop 0
	v_add_f32_e32 v65, 1.0, v65
	v_rcp_f32_e32 v75, v65
	s_nop 0
	v_mul_f32_e64 v72, v74, v72
	v_mul_f32_e64 v73, v75, v73
	s_nop 0
	v_mul_f32_e64 v72, v72, v82
	v_mul_f32_e64 v73, v73, v83
	s_nop 0
	v_cvt_pk_bf16_f32 v65, v72, v73
	v_lshlrev_b32_e32 v72, 16, v70
	v_and_b32_e32 v73, 0xffff0000, v70
	v_mul_f32_e32 v70, 0xbfb8aa3b, v72
	v_exp_f32_e32 v70, v70
	s_nop 0
	v_add_f32_e32 v70, 1.0, v70
	v_rcp_f32_e32 v74, v70
	v_mul_f32_e32 v70, 0xbfb8aa3b, v73
	v_exp_f32_e32 v70, v70
	s_nop 0
	v_add_f32_e32 v70, 1.0, v70
	v_rcp_f32_e32 v75, v70
	s_nop 0
	v_mul_f32_e64 v72, v74, v72
	v_mul_f32_e64 v73, v75, v73
	s_nop 0
	v_mul_f32_e64 v72, v72, v76
	v_mul_f32_e64 v73, v73, v77
	s_nop 0
	v_cvt_pk_bf16_f32 v70, v72, v73
	v_lshlrev_b32_e32 v72, 16, v66
	v_and_b32_e32 v73, 0xffff0000, v66
	v_mul_f32_e32 v66, 0xbfb8aa3b, v72
	v_exp_f32_e32 v66, v66
	s_nop 0
	v_add_f32_e32 v66, 1.0, v66
	v_rcp_f32_e32 v74, v66
	v_mul_f32_e32 v66, 0xbfb8aa3b, v73
	v_exp_f32_e32 v66, v66
	s_nop 0
	v_add_f32_e32 v66, 1.0, v66
	v_rcp_f32_e32 v75, v66
	s_nop 0
	v_mul_f32_e64 v72, v74, v72
	v_mul_f32_e64 v73, v75, v73
	s_waitcnt lgkmcnt(0)
	v_mul_f32_e64 v72, v72, v84
	v_mul_f32_e64 v73, v73, v85
	s_nop 0
	v_cvt_pk_bf16_f32 v66, v72, v73
	v_lshlrev_b32_e32 v72, 16, v71
	v_and_b32_e32 v73, 0xffff0000, v71
	v_mul_f32_e32 v71, 0xbfb8aa3b, v72
	v_exp_f32_e32 v71, v71
	s_nop 0
	v_add_f32_e32 v71, 1.0, v71
	v_rcp_f32_e32 v74, v71
	v_mul_f32_e32 v71, 0xbfb8aa3b, v73
	v_exp_f32_e32 v71, v71
	s_nop 0
	v_add_f32_e32 v71, 1.0, v71
	v_rcp_f32_e32 v75, v71
	s_nop 0
	v_mul_f32_e64 v72, v74, v72
	v_mul_f32_e64 v73, v75, v73
	s_nop 0
	v_mul_f32_e64 v72, v72, v78
	v_mul_f32_e64 v73, v73, v79
	s_nop 0
	v_cvt_pk_bf16_f32 v71, v72, v73
	v_lshlrev_b32_e32 v72, 16, v67
	v_and_b32_e32 v73, 0xffff0000, v67
	v_mul_f32_e32 v67, 0xbfb8aa3b, v72
	v_exp_f32_e32 v67, v67
	s_nop 0
	v_add_f32_e32 v67, 1.0, v67
	v_rcp_f32_e32 v74, v67
	v_mul_f32_e32 v67, 0xbfb8aa3b, v73
	v_exp_f32_e32 v67, v67
	s_nop 0
	v_add_f32_e32 v67, 1.0, v67
	v_rcp_f32_e32 v75, v67
	s_nop 0
	v_mul_f32_e64 v72, v74, v72
	v_mul_f32_e64 v73, v75, v73
	s_nop 0
	v_mul_f32_e64 v72, v72, v86
	v_mul_f32_e64 v73, v73, v87
	s_nop 0
	v_cvt_pk_bf16_f32 v67, v72, v73
	v_mad_i64_i32 v[72:73], s[16:17], v202, s90, v[180:181]
	global_store_dwordx4 v[72:73], v[68:71], off
	s_nop 1
	v_mad_i64_i32 v[68:69], s[16:17], v202, s90, v[182:183]
	v_add_co_u32_e32 v68, vcc, 0x17320000, v68
	s_nop 1
	v_addc_co_u32_e32 v69, vcc, 0, v69, vcc
	global_store_dwordx4 v[68:69], v[64:67], off offset:16
	s_cbranch_scc0 .LBB0_1674
	s_branch .LBB0_1657
